# 4th round of P1 items dealt starting from the waves that have no P0 item (they wait for the first barrier's release anyway)
# baseline (speedup 1.0000x reference)
; __global__ void __launch_bounds__(NWAVES * 64, 2) fwd(Args a) {
;     ...
;         constexpr int I0 = 16 * 64, I1 = I0 + 8 * 32, I2 = I1 + 16 * 176, I4 = I2 + 44 * 32, I5 = I4 + 4 * 16 * 16, I6 = I5 + 88, I7 = I6 + NBATCH * 16;
;         for (int it = gw; it < I7; it += NGW) {
.LBB0_67:
	s_add_i32 s33, s33, s76
	s_cmpk_lt_i32 s33, 0x1800
	s_cbranch_scc1 .Lit_norm
	s_cmpk_gt_i32 s33, 0x1fff
	s_cbranch_scc1 .LBB0_96
	s_sub_i32 s33, s33, 0x1800
	s_addk_i32 s33, 0x200
	s_and_b32 s33, s33, 0x7ff
	s_addk_i32 s33, 0x1800
.Lit_norm:
	s_sub_i32 s4, s33, s77
	s_add_i32 s4, s4, s98
	s_lshl_b32 s13, s33, 6
	s_cmpk_gt_i32 s33, 0x1a77
	s_cbranch_scc1 .LBB0_96
